# indexer radix passes 1-3: four keys tested per branch (xor with shifted prefix, min3/min, one compare), bin index by v_bfe + cndmask on the matching path
# speedup vs baseline: 1.0077x; 1.0024x over previous
; #define SEL_HADD(idx_) __hip_atomic_fetch_add(&hist[(idx_)], 1u, __ATOMIC_RELAXED, __HIP_MEMORY_SCOPE_WORKGROUP)
; __device__ __forceinline__ void sel_unit(LAS char* lds, int b, int u, const bf16_t* QI, const bf16_t* KIDX, const float* WIDX, unsigned long long* MASK) {
;     ...
;     for (int pass = 1; pass < 4; ++pass) {
;         const int shift = 24 - 8 * pass;
;         { const int t_ = opaque_tid(); for (int i = t_; i < 4096; i += 512) hist[i] = 0u; }
;         __syncthreads();
;         const unsigned pf = pref[q16];
;         unsigned zz = 0u; asm volatile("" : "+v"(zz));
; #pragma unroll
;         for (int j = 0; j < 8; ++j) if (j < nj) {
; #pragma unroll
;             for (int kb = 0; kb < 4; ++kb)
; #pragma unroll
;                 for (int i = 0; i < 4; ++i) { const unsigned k = sc[j][kb][i] | zz; SEL_HADD((((k >> (shift + 8)) == pf) ? ((k >> shift) & 255u) * 16 : 4096u) + q16); __builtin_amdgcn_sched_barrier(0); }
;         }
.LBB0_709:
	s_or_b64 exec, exec, s[2:3]
	s_waitcnt lgkmcnt(0)
	s_barrier
	ds_read_b32 v2, v60 offset:34880
	s_lshl_b32 s2, s21, 3
	s_sub_i32 s16, 24, s2
	v_mov_b32_e32 v3, 0
	s_sub_i32 s17, 32, s2
	s_waitcnt lgkmcnt(0)
	v_lshlrev_b32_e32 v34, s17, v2
	v_mov_b32_e32 v35, 0x100
	s_lshl_b32 s76, 1, s17
	s_and_b64 vcc, exec, s[22:23]
	s_cbranch_vccz .LBB0_711
	v_xor_b32_e32 v36, v34, v62
	v_xor_b32_e32 v37, v34, v61
	v_xor_b32_e32 v38, v34, v64
	v_xor_b32_e32 v39, v34, v63
	v_min3_u32 v40, v36, v37, v38
	v_min_u32_e32 v40, v40, v39
	v_cmp_gt_u32_e32 vcc, s76, v40
	s_cbranch_vccz .Lsel_grp_1
	v_cmp_gt_u32_e32 vcc, s76, v36
	v_cmp_gt_u32_e64 s[28:29], s76, v37
	v_cmp_gt_u32_e64 s[44:45], s76, v38
	v_cmp_gt_u32_e64 s[74:75], s76, v39
	v_bfe_u32 v36, v62, s16, 8
	v_bfe_u32 v37, v61, s16, 8
	v_bfe_u32 v38, v64, s16, 8
	v_bfe_u32 v39, v63, s16, 8
	v_cndmask_b32_e32 v36, v35, v36, vcc
	v_cndmask_b32_e64 v37, v35, v37, s[28:29]
	v_cndmask_b32_e64 v38, v35, v38, s[44:45]
	v_cndmask_b32_e64 v39, v35, v39, s[74:75]
	v_lshl_add_u32 v36, v36, 6, v0
	v_lshl_add_u32 v37, v37, 6, v0
	v_lshl_add_u32 v38, v38, 6, v0
	v_lshl_add_u32 v39, v39, 6, v0
	ds_add_u32 v36, v205 offset:16384
	ds_add_u32 v37, v205 offset:16384
	ds_add_u32 v38, v205 offset:16384
	ds_add_u32 v39, v205 offset:16384
.Lsel_grp_1:
	v_xor_b32_e32 v36, v34, v66
	v_xor_b32_e32 v37, v34, v65
	v_xor_b32_e32 v38, v34, v68
	v_xor_b32_e32 v39, v34, v67
	v_min3_u32 v40, v36, v37, v38
	v_min_u32_e32 v40, v40, v39
	v_cmp_gt_u32_e32 vcc, s76, v40
	s_cbranch_vccz .Lsel_grp_2
	v_cmp_gt_u32_e32 vcc, s76, v36
	v_cmp_gt_u32_e64 s[28:29], s76, v37
	v_cmp_gt_u32_e64 s[44:45], s76, v38
	v_cmp_gt_u32_e64 s[74:75], s76, v39
	v_bfe_u32 v36, v66, s16, 8
	v_bfe_u32 v37, v65, s16, 8
	v_bfe_u32 v38, v68, s16, 8
	v_bfe_u32 v39, v67, s16, 8
	v_cndmask_b32_e32 v36, v35, v36, vcc
	v_cndmask_b32_e64 v37, v35, v37, s[28:29]
	v_cndmask_b32_e64 v38, v35, v38, s[44:45]
	v_cndmask_b32_e64 v39, v35, v39, s[74:75]
	v_lshl_add_u32 v36, v36, 6, v0
	v_lshl_add_u32 v37, v37, 6, v0
	v_lshl_add_u32 v38, v38, 6, v0
	v_lshl_add_u32 v39, v39, 6, v0
	ds_add_u32 v36, v205 offset:16384
	ds_add_u32 v37, v205 offset:16384
	ds_add_u32 v38, v205 offset:16384
	ds_add_u32 v39, v205 offset:16384
.Lsel_grp_2:
	v_xor_b32_e32 v36, v34, v70
	v_xor_b32_e32 v37, v34, v69
	v_xor_b32_e32 v38, v34, v72
	v_xor_b32_e32 v39, v34, v71
	v_min3_u32 v40, v36, v37, v38
	v_min_u32_e32 v40, v40, v39
	v_cmp_gt_u32_e32 vcc, s76, v40
	s_cbranch_vccz .Lsel_grp_3
	v_cmp_gt_u32_e32 vcc, s76, v36
	v_cmp_gt_u32_e64 s[28:29], s76, v37
	v_cmp_gt_u32_e64 s[44:45], s76, v38
	v_cmp_gt_u32_e64 s[74:75], s76, v39
	v_bfe_u32 v36, v70, s16, 8
	v_bfe_u32 v37, v69, s16, 8
	v_bfe_u32 v38, v72, s16, 8
	v_bfe_u32 v39, v71, s16, 8
	v_cndmask_b32_e32 v36, v35, v36, vcc
	v_cndmask_b32_e64 v37, v35, v37, s[28:29]
	v_cndmask_b32_e64 v38, v35, v38, s[44:45]
	v_cndmask_b32_e64 v39, v35, v39, s[74:75]
	v_lshl_add_u32 v36, v36, 6, v0
	v_lshl_add_u32 v37, v37, 6, v0
	v_lshl_add_u32 v38, v38, 6, v0
	v_lshl_add_u32 v39, v39, 6, v0
	ds_add_u32 v36, v205 offset:16384
	ds_add_u32 v37, v205 offset:16384
	ds_add_u32 v38, v205 offset:16384
	ds_add_u32 v39, v205 offset:16384
.Lsel_grp_3:
	v_xor_b32_e32 v36, v34, v74
	v_xor_b32_e32 v37, v34, v73
	v_xor_b32_e32 v38, v34, v76
	v_xor_b32_e32 v39, v34, v75
	v_min3_u32 v40, v36, v37, v38
	v_min_u32_e32 v40, v40, v39
	v_cmp_gt_u32_e32 vcc, s76, v40
	s_cbranch_vccz .Lsel_grp_4
	v_cmp_gt_u32_e32 vcc, s76, v36
	v_cmp_gt_u32_e64 s[28:29], s76, v37
	v_cmp_gt_u32_e64 s[44:45], s76, v38
	v_cmp_gt_u32_e64 s[74:75], s76, v39
	v_bfe_u32 v36, v74, s16, 8
	v_bfe_u32 v37, v73, s16, 8
	v_bfe_u32 v38, v76, s16, 8
	v_bfe_u32 v39, v75, s16, 8
	v_cndmask_b32_e32 v36, v35, v36, vcc
	v_cndmask_b32_e64 v37, v35, v37, s[28:29]
	v_cndmask_b32_e64 v38, v35, v38, s[44:45]
	v_cndmask_b32_e64 v39, v35, v39, s[74:75]
	v_lshl_add_u32 v36, v36, 6, v0
	v_lshl_add_u32 v37, v37, 6, v0
	v_lshl_add_u32 v38, v38, 6, v0
	v_lshl_add_u32 v39, v39, 6, v0
	ds_add_u32 v36, v205 offset:16384
	ds_add_u32 v37, v205 offset:16384
	ds_add_u32 v38, v205 offset:16384
	ds_add_u32 v39, v205 offset:16384
; #define SEL_HADD(idx_) __hip_atomic_fetch_add(&hist[(idx_)], 1u, __ATOMIC_RELAXED, __HIP_MEMORY_SCOPE_WORKGROUP)
; __device__ __forceinline__ void sel_unit(LAS char* lds, int b, int u, const bf16_t* QI, const bf16_t* KIDX, const float* WIDX, unsigned long long* MASK) {
;     ...
;         for (int j = 0; j < 8; ++j) if (j < nj) {
; #pragma unroll
;             for (int kb = 0; kb < 4; ++kb)
; #pragma unroll
;                 for (int i = 0; i < 4; ++i) { const unsigned k = sc[j][kb][i] | zz; SEL_HADD((((k >> (shift + 8)) == pf) ? ((k >> shift) & 255u) * 16 : 4096u) + q16); __builtin_amdgcn_sched_barrier(0); }
.Lsel_grp_4:
.LBB0_711:
	v_cndmask_b32_e64 v4, 0, 1, s[18:19]
	v_cmp_ne_u32_e64 s[2:3], 1, v4
	s_andn2_b64 vcc, exec, s[18:19]
	s_cbranch_vccnz .LBB0_741
	v_xor_b32_e32 v36, v34, v78
	v_xor_b32_e32 v37, v34, v77
	v_xor_b32_e32 v38, v34, v80
	v_xor_b32_e32 v39, v34, v79
	v_min3_u32 v40, v36, v37, v38
	v_min_u32_e32 v40, v40, v39
	v_cmp_gt_u32_e32 vcc, s76, v40
	s_cbranch_vccz .Lsel_grp_5
	v_cmp_gt_u32_e32 vcc, s76, v36
	v_cmp_gt_u32_e64 s[28:29], s76, v37
	v_cmp_gt_u32_e64 s[44:45], s76, v38
	v_cmp_gt_u32_e64 s[74:75], s76, v39
	v_bfe_u32 v36, v78, s16, 8
	v_bfe_u32 v37, v77, s16, 8
	v_bfe_u32 v38, v80, s16, 8
	v_bfe_u32 v39, v79, s16, 8
	v_cndmask_b32_e32 v36, v35, v36, vcc
	v_cndmask_b32_e64 v37, v35, v37, s[28:29]
	v_cndmask_b32_e64 v38, v35, v38, s[44:45]
	v_cndmask_b32_e64 v39, v35, v39, s[74:75]
	v_lshl_add_u32 v36, v36, 6, v0
	v_lshl_add_u32 v37, v37, 6, v0
	v_lshl_add_u32 v38, v38, 6, v0
	v_lshl_add_u32 v39, v39, 6, v0
	ds_add_u32 v36, v205 offset:16384
	ds_add_u32 v37, v205 offset:16384
	ds_add_u32 v38, v205 offset:16384
	ds_add_u32 v39, v205 offset:16384
.Lsel_grp_5:
	v_xor_b32_e32 v36, v34, v82
	v_xor_b32_e32 v37, v34, v81
	v_xor_b32_e32 v38, v34, v84
	v_xor_b32_e32 v39, v34, v83
	v_min3_u32 v40, v36, v37, v38
	v_min_u32_e32 v40, v40, v39
	v_cmp_gt_u32_e32 vcc, s76, v40
	s_cbranch_vccz .Lsel_grp_6
	v_cmp_gt_u32_e32 vcc, s76, v36
	v_cmp_gt_u32_e64 s[28:29], s76, v37
	v_cmp_gt_u32_e64 s[44:45], s76, v38
	v_cmp_gt_u32_e64 s[74:75], s76, v39
	v_bfe_u32 v36, v82, s16, 8
	v_bfe_u32 v37, v81, s16, 8
	v_bfe_u32 v38, v84, s16, 8
	v_bfe_u32 v39, v83, s16, 8
	v_cndmask_b32_e32 v36, v35, v36, vcc
	v_cndmask_b32_e64 v37, v35, v37, s[28:29]
	v_cndmask_b32_e64 v38, v35, v38, s[44:45]
	v_cndmask_b32_e64 v39, v35, v39, s[74:75]
	v_lshl_add_u32 v36, v36, 6, v0
	v_lshl_add_u32 v37, v37, 6, v0
	v_lshl_add_u32 v38, v38, 6, v0
	v_lshl_add_u32 v39, v39, 6, v0
	ds_add_u32 v36, v205 offset:16384
	ds_add_u32 v37, v205 offset:16384
	ds_add_u32 v38, v205 offset:16384
	ds_add_u32 v39, v205 offset:16384
.Lsel_grp_6:
	v_xor_b32_e32 v36, v34, v86
	v_xor_b32_e32 v37, v34, v85
	v_xor_b32_e32 v38, v34, v88
	v_xor_b32_e32 v39, v34, v87
	v_min3_u32 v40, v36, v37, v38
	v_min_u32_e32 v40, v40, v39
	v_cmp_gt_u32_e32 vcc, s76, v40
	s_cbranch_vccz .Lsel_grp_7
	v_cmp_gt_u32_e32 vcc, s76, v36
	v_cmp_gt_u32_e64 s[28:29], s76, v37
	v_cmp_gt_u32_e64 s[44:45], s76, v38
	v_cmp_gt_u32_e64 s[74:75], s76, v39
	v_bfe_u32 v36, v86, s16, 8
	v_bfe_u32 v37, v85, s16, 8
	v_bfe_u32 v38, v88, s16, 8
	v_bfe_u32 v39, v87, s16, 8
	v_cndmask_b32_e32 v36, v35, v36, vcc
	v_cndmask_b32_e64 v37, v35, v37, s[28:29]
	v_cndmask_b32_e64 v38, v35, v38, s[44:45]
	v_cndmask_b32_e64 v39, v35, v39, s[74:75]
	v_lshl_add_u32 v36, v36, 6, v0
	v_lshl_add_u32 v37, v37, 6, v0
	v_lshl_add_u32 v38, v38, 6, v0
	v_lshl_add_u32 v39, v39, 6, v0
	ds_add_u32 v36, v205 offset:16384
	ds_add_u32 v37, v205 offset:16384
	ds_add_u32 v38, v205 offset:16384
	ds_add_u32 v39, v205 offset:16384
.Lsel_grp_7:
	v_xor_b32_e32 v36, v34, v90
	v_xor_b32_e32 v37, v34, v89
	v_xor_b32_e32 v38, v34, v92
	v_xor_b32_e32 v39, v34, v91
	v_min3_u32 v40, v36, v37, v38
	v_min_u32_e32 v40, v40, v39
	v_cmp_gt_u32_e32 vcc, s76, v40
	s_cbranch_vccz .Lsel_grp_8
	v_cmp_gt_u32_e32 vcc, s76, v36
	v_cmp_gt_u32_e64 s[28:29], s76, v37
	v_cmp_gt_u32_e64 s[44:45], s76, v38
	v_cmp_gt_u32_e64 s[74:75], s76, v39
	v_bfe_u32 v36, v90, s16, 8
	v_bfe_u32 v37, v89, s16, 8
	v_bfe_u32 v38, v92, s16, 8
	v_bfe_u32 v39, v91, s16, 8
	v_cndmask_b32_e32 v36, v35, v36, vcc
	v_cndmask_b32_e64 v37, v35, v37, s[28:29]
	v_cndmask_b32_e64 v38, v35, v38, s[44:45]
	v_cndmask_b32_e64 v39, v35, v39, s[74:75]
	v_lshl_add_u32 v36, v36, 6, v0
	v_lshl_add_u32 v37, v37, 6, v0
	v_lshl_add_u32 v38, v38, 6, v0
	v_lshl_add_u32 v39, v39, 6, v0
	ds_add_u32 v36, v205 offset:16384
	ds_add_u32 v37, v205 offset:16384
	ds_add_u32 v38, v205 offset:16384
	ds_add_u32 v39, v205 offset:16384

; #define SEL_HADD(idx_) __hip_atomic_fetch_add(&hist[(idx_)], 1u, __ATOMIC_RELAXED, __HIP_MEMORY_SCOPE_WORKGROUP)
; __device__ __forceinline__ void sel_unit(LAS char* lds, int b, int u, const bf16_t* QI, const bf16_t* KIDX, const float* WIDX, unsigned long long* MASK) {
;     ...
;         for (int j = 0; j < 8; ++j) if (j < nj) {
; #pragma unroll
;             for (int kb = 0; kb < 4; ++kb)
; #pragma unroll
;                 for (int i = 0; i < 4; ++i) { const unsigned k = sc[j][kb][i] | zz; SEL_HADD((((k >> (shift + 8)) == pf) ? ((k >> shift) & 255u) * 16 : 4096u) + q16); __builtin_amdgcn_sched_barrier(0); }
.LBB0_714:
	v_xor_b32_e32 v36, v34, v110
	v_xor_b32_e32 v37, v34, v109
	v_xor_b32_e32 v38, v34, v112
	v_xor_b32_e32 v39, v34, v111
	v_min3_u32 v40, v36, v37, v38
	v_min_u32_e32 v40, v40, v39
	v_cmp_gt_u32_e32 vcc, s76, v40
	s_cbranch_vccz .Lsel_grp_9
	v_cmp_gt_u32_e32 vcc, s76, v36
	v_cmp_gt_u32_e64 s[28:29], s76, v37
	v_cmp_gt_u32_e64 s[44:45], s76, v38
	v_cmp_gt_u32_e64 s[74:75], s76, v39
	v_bfe_u32 v36, v110, s16, 8
	v_bfe_u32 v37, v109, s16, 8
	v_bfe_u32 v38, v112, s16, 8
	v_bfe_u32 v39, v111, s16, 8
	v_cndmask_b32_e32 v36, v35, v36, vcc
	v_cndmask_b32_e64 v37, v35, v37, s[28:29]
	v_cndmask_b32_e64 v38, v35, v38, s[44:45]
	v_cndmask_b32_e64 v39, v35, v39, s[74:75]
	v_lshl_add_u32 v36, v36, 6, v0
	v_lshl_add_u32 v37, v37, 6, v0
	v_lshl_add_u32 v38, v38, 6, v0
	v_lshl_add_u32 v39, v39, 6, v0
	ds_add_u32 v36, v205 offset:16384
	ds_add_u32 v37, v205 offset:16384
	ds_add_u32 v38, v205 offset:16384
	ds_add_u32 v39, v205 offset:16384
.Lsel_grp_9:
	v_xor_b32_e32 v36, v34, v114
	v_xor_b32_e32 v37, v34, v113
	v_xor_b32_e32 v38, v34, v116
	v_xor_b32_e32 v39, v34, v115
	v_min3_u32 v40, v36, v37, v38
	v_min_u32_e32 v40, v40, v39
	v_cmp_gt_u32_e32 vcc, s76, v40
	s_cbranch_vccz .Lsel_grp_10
	v_cmp_gt_u32_e32 vcc, s76, v36
	v_cmp_gt_u32_e64 s[28:29], s76, v37
	v_cmp_gt_u32_e64 s[44:45], s76, v38
	v_cmp_gt_u32_e64 s[74:75], s76, v39
	v_bfe_u32 v36, v114, s16, 8
	v_bfe_u32 v37, v113, s16, 8
	v_bfe_u32 v38, v116, s16, 8
	v_bfe_u32 v39, v115, s16, 8
	v_cndmask_b32_e32 v36, v35, v36, vcc
	v_cndmask_b32_e64 v37, v35, v37, s[28:29]
	v_cndmask_b32_e64 v38, v35, v38, s[44:45]
	v_cndmask_b32_e64 v39, v35, v39, s[74:75]
	v_lshl_add_u32 v36, v36, 6, v0
	v_lshl_add_u32 v37, v37, 6, v0
	v_lshl_add_u32 v38, v38, 6, v0
	v_lshl_add_u32 v39, v39, 6, v0
	ds_add_u32 v36, v205 offset:16384
	ds_add_u32 v37, v205 offset:16384
	ds_add_u32 v38, v205 offset:16384
	ds_add_u32 v39, v205 offset:16384
.Lsel_grp_10:
	v_xor_b32_e32 v36, v34, v118
	v_xor_b32_e32 v37, v34, v117
	v_xor_b32_e32 v38, v34, v120
	v_xor_b32_e32 v39, v34, v119
	v_min3_u32 v40, v36, v37, v38
	v_min_u32_e32 v40, v40, v39
	v_cmp_gt_u32_e32 vcc, s76, v40
	s_cbranch_vccz .Lsel_grp_11
	v_cmp_gt_u32_e32 vcc, s76, v36
	v_cmp_gt_u32_e64 s[28:29], s76, v37
	v_cmp_gt_u32_e64 s[44:45], s76, v38
	v_cmp_gt_u32_e64 s[74:75], s76, v39
	v_bfe_u32 v36, v118, s16, 8
	v_bfe_u32 v37, v117, s16, 8
	v_bfe_u32 v38, v120, s16, 8
	v_bfe_u32 v39, v119, s16, 8
	v_cndmask_b32_e32 v36, v35, v36, vcc
	v_cndmask_b32_e64 v37, v35, v37, s[28:29]
	v_cndmask_b32_e64 v38, v35, v38, s[44:45]
	v_cndmask_b32_e64 v39, v35, v39, s[74:75]
	v_lshl_add_u32 v36, v36, 6, v0
	v_lshl_add_u32 v37, v37, 6, v0
	v_lshl_add_u32 v38, v38, 6, v0
	v_lshl_add_u32 v39, v39, 6, v0
	ds_add_u32 v36, v205 offset:16384
	ds_add_u32 v37, v205 offset:16384
	ds_add_u32 v38, v205 offset:16384
	ds_add_u32 v39, v205 offset:16384
.Lsel_grp_11:
	v_xor_b32_e32 v36, v34, v122
	v_xor_b32_e32 v37, v34, v121
	v_xor_b32_e32 v38, v34, v124
	v_xor_b32_e32 v39, v34, v123
	v_min3_u32 v40, v36, v37, v38
	v_min_u32_e32 v40, v40, v39
	v_cmp_gt_u32_e32 vcc, s76, v40
	s_cbranch_vccz .Lsel_grp_12
	v_cmp_gt_u32_e32 vcc, s76, v36
	v_cmp_gt_u32_e64 s[28:29], s76, v37
	v_cmp_gt_u32_e64 s[44:45], s76, v38
	v_cmp_gt_u32_e64 s[74:75], s76, v39
	v_bfe_u32 v36, v122, s16, 8
	v_bfe_u32 v37, v121, s16, 8
	v_bfe_u32 v38, v124, s16, 8
	v_bfe_u32 v39, v123, s16, 8
	v_cndmask_b32_e32 v36, v35, v36, vcc
	v_cndmask_b32_e64 v37, v35, v37, s[28:29]
	v_cndmask_b32_e64 v38, v35, v38, s[44:45]
	v_cndmask_b32_e64 v39, v35, v39, s[74:75]
	v_lshl_add_u32 v36, v36, 6, v0
	v_lshl_add_u32 v37, v37, 6, v0
	v_lshl_add_u32 v38, v38, 6, v0
	v_lshl_add_u32 v39, v39, 6, v0
	ds_add_u32 v36, v205 offset:16384
	ds_add_u32 v37, v205 offset:16384
	ds_add_u32 v38, v205 offset:16384
	ds_add_u32 v39, v205 offset:16384

; #define SEL_HADD(idx_) __hip_atomic_fetch_add(&hist[(idx_)], 1u, __ATOMIC_RELAXED, __HIP_MEMORY_SCOPE_WORKGROUP)
; __device__ __forceinline__ void sel_unit(LAS char* lds, int b, int u, const bf16_t* QI, const bf16_t* KIDX, const float* WIDX, unsigned long long* MASK) {
;     ...
;         for (int j = 0; j < 8; ++j) if (j < nj) {
; #pragma unroll
;             for (int kb = 0; kb < 4; ++kb)
; #pragma unroll
;                 for (int i = 0; i < 4; ++i) { const unsigned k = sc[j][kb][i] | zz; SEL_HADD((((k >> (shift + 8)) == pf) ? ((k >> shift) & 255u) * 16 : 4096u) + q16); __builtin_amdgcn_sched_barrier(0); }
.LBB0_716:
	v_xor_b32_e32 v36, v34, v143
	v_xor_b32_e32 v37, v34, v142
	v_xor_b32_e32 v38, v34, v145
	v_xor_b32_e32 v39, v34, v144
	v_min3_u32 v40, v36, v37, v38
	v_min_u32_e32 v40, v40, v39
	v_cmp_gt_u32_e32 vcc, s76, v40
	s_cbranch_vccz .Lsel_grp_13
	v_cmp_gt_u32_e32 vcc, s76, v36
	v_cmp_gt_u32_e64 s[28:29], s76, v37
	v_cmp_gt_u32_e64 s[44:45], s76, v38
	v_cmp_gt_u32_e64 s[74:75], s76, v39
	v_bfe_u32 v36, v143, s16, 8
	v_bfe_u32 v37, v142, s16, 8
	v_bfe_u32 v38, v145, s16, 8
	v_bfe_u32 v39, v144, s16, 8
	v_cndmask_b32_e32 v36, v35, v36, vcc
	v_cndmask_b32_e64 v37, v35, v37, s[28:29]
	v_cndmask_b32_e64 v38, v35, v38, s[44:45]
	v_cndmask_b32_e64 v39, v35, v39, s[74:75]
	v_lshl_add_u32 v36, v36, 6, v0
	v_lshl_add_u32 v37, v37, 6, v0
	v_lshl_add_u32 v38, v38, 6, v0
	v_lshl_add_u32 v39, v39, 6, v0
	ds_add_u32 v36, v205 offset:16384
	ds_add_u32 v37, v205 offset:16384
	ds_add_u32 v38, v205 offset:16384
	ds_add_u32 v39, v205 offset:16384
.Lsel_grp_13:
	v_xor_b32_e32 v36, v34, v147
	v_xor_b32_e32 v37, v34, v146
	v_xor_b32_e32 v38, v34, v149
	v_xor_b32_e32 v39, v34, v148
	v_min3_u32 v40, v36, v37, v38
	v_min_u32_e32 v40, v40, v39
	v_cmp_gt_u32_e32 vcc, s76, v40
	s_cbranch_vccz .Lsel_grp_14
	v_cmp_gt_u32_e32 vcc, s76, v36
	v_cmp_gt_u32_e64 s[28:29], s76, v37
	v_cmp_gt_u32_e64 s[44:45], s76, v38
	v_cmp_gt_u32_e64 s[74:75], s76, v39
	v_bfe_u32 v36, v147, s16, 8
	v_bfe_u32 v37, v146, s16, 8
	v_bfe_u32 v38, v149, s16, 8
	v_bfe_u32 v39, v148, s16, 8
	v_cndmask_b32_e32 v36, v35, v36, vcc
	v_cndmask_b32_e64 v37, v35, v37, s[28:29]
	v_cndmask_b32_e64 v38, v35, v38, s[44:45]
	v_cndmask_b32_e64 v39, v35, v39, s[74:75]
	v_lshl_add_u32 v36, v36, 6, v0
	v_lshl_add_u32 v37, v37, 6, v0
	v_lshl_add_u32 v38, v38, 6, v0
	v_lshl_add_u32 v39, v39, 6, v0
	ds_add_u32 v36, v205 offset:16384
	ds_add_u32 v37, v205 offset:16384
	ds_add_u32 v38, v205 offset:16384
	ds_add_u32 v39, v205 offset:16384
.Lsel_grp_14:
	v_xor_b32_e32 v36, v34, v178
	v_xor_b32_e32 v37, v34, v177
	v_xor_b32_e32 v38, v34, v186
	v_xor_b32_e32 v39, v34, v181
	v_min3_u32 v40, v36, v37, v38
	v_min_u32_e32 v40, v40, v39
	v_cmp_gt_u32_e32 vcc, s76, v40
	s_cbranch_vccz .Lsel_grp_15
	v_cmp_gt_u32_e32 vcc, s76, v36
	v_cmp_gt_u32_e64 s[28:29], s76, v37
	v_cmp_gt_u32_e64 s[44:45], s76, v38
	v_cmp_gt_u32_e64 s[74:75], s76, v39
	v_bfe_u32 v36, v178, s16, 8
	v_bfe_u32 v37, v177, s16, 8
	v_bfe_u32 v38, v186, s16, 8
	v_bfe_u32 v39, v181, s16, 8
	v_cndmask_b32_e32 v36, v35, v36, vcc
	v_cndmask_b32_e64 v37, v35, v37, s[28:29]
	v_cndmask_b32_e64 v38, v35, v38, s[44:45]
	v_cndmask_b32_e64 v39, v35, v39, s[74:75]
	v_lshl_add_u32 v36, v36, 6, v0
	v_lshl_add_u32 v37, v37, 6, v0
	v_lshl_add_u32 v38, v38, 6, v0
	v_lshl_add_u32 v39, v39, 6, v0
	ds_add_u32 v36, v205 offset:16384
	ds_add_u32 v37, v205 offset:16384
	ds_add_u32 v38, v205 offset:16384
	ds_add_u32 v39, v205 offset:16384
.Lsel_grp_15:
	v_xor_b32_e32 v36, v34, v188
	v_xor_b32_e32 v37, v34, v187
	v_xor_b32_e32 v38, v34, v190
	v_xor_b32_e32 v39, v34, v189
	v_min3_u32 v40, v36, v37, v38
	v_min_u32_e32 v40, v40, v39
	v_cmp_gt_u32_e32 vcc, s76, v40
	s_cbranch_vccz .Lsel_grp_16
	v_cmp_gt_u32_e32 vcc, s76, v36
	v_cmp_gt_u32_e64 s[28:29], s76, v37
	v_cmp_gt_u32_e64 s[44:45], s76, v38
	v_cmp_gt_u32_e64 s[74:75], s76, v39
	v_bfe_u32 v36, v188, s16, 8
	v_bfe_u32 v37, v187, s16, 8
	v_bfe_u32 v38, v190, s16, 8
	v_bfe_u32 v39, v189, s16, 8
	v_cndmask_b32_e32 v36, v35, v36, vcc
	v_cndmask_b32_e64 v37, v35, v37, s[28:29]
	v_cndmask_b32_e64 v38, v35, v38, s[44:45]
	v_cndmask_b32_e64 v39, v35, v39, s[74:75]
	v_lshl_add_u32 v36, v36, 6, v0
	v_lshl_add_u32 v37, v37, 6, v0
	v_lshl_add_u32 v38, v38, 6, v0
	v_lshl_add_u32 v39, v39, 6, v0
	ds_add_u32 v36, v205 offset:16384
	ds_add_u32 v37, v205 offset:16384
	ds_add_u32 v38, v205 offset:16384
	ds_add_u32 v39, v205 offset:16384

; #define SEL_HADD(idx_) __hip_atomic_fetch_add(&hist[(idx_)], 1u, __ATOMIC_RELAXED, __HIP_MEMORY_SCOPE_WORKGROUP)
; __device__ __forceinline__ void sel_unit(LAS char* lds, int b, int u, const bf16_t* QI, const bf16_t* KIDX, const float* WIDX, unsigned long long* MASK) {
;     ...
;         for (int j = 0; j < 8; ++j) if (j < nj) {
; #pragma unroll
;             for (int kb = 0; kb < 4; ++kb)
; #pragma unroll
;                 for (int i = 0; i < 4; ++i) { const unsigned k = sc[j][kb][i] | zz; SEL_HADD((((k >> (shift + 8)) == pf) ? ((k >> shift) & 255u) * 16 : 4096u) + q16); __builtin_amdgcn_sched_barrier(0); }
.LBB0_718:
	v_xor_b32_e32 v36, v34, v222
	v_xor_b32_e32 v37, v34, v221
	v_xor_b32_e32 v38, v34, v224
	v_xor_b32_e32 v39, v34, v223
	v_min3_u32 v40, v36, v37, v38
	v_min_u32_e32 v40, v40, v39
	v_cmp_gt_u32_e32 vcc, s76, v40
	s_cbranch_vccz .Lsel_grp_17
	v_cmp_gt_u32_e32 vcc, s76, v36
	v_cmp_gt_u32_e64 s[28:29], s76, v37
	v_cmp_gt_u32_e64 s[44:45], s76, v38
	v_cmp_gt_u32_e64 s[74:75], s76, v39
	v_bfe_u32 v36, v222, s16, 8
	v_bfe_u32 v37, v221, s16, 8
	v_bfe_u32 v38, v224, s16, 8
	v_bfe_u32 v39, v223, s16, 8
	v_cndmask_b32_e32 v36, v35, v36, vcc
	v_cndmask_b32_e64 v37, v35, v37, s[28:29]
	v_cndmask_b32_e64 v38, v35, v38, s[44:45]
	v_cndmask_b32_e64 v39, v35, v39, s[74:75]
	v_lshl_add_u32 v36, v36, 6, v0
	v_lshl_add_u32 v37, v37, 6, v0
	v_lshl_add_u32 v38, v38, 6, v0
	v_lshl_add_u32 v39, v39, 6, v0
	ds_add_u32 v36, v205 offset:16384
	ds_add_u32 v37, v205 offset:16384
	ds_add_u32 v38, v205 offset:16384
	ds_add_u32 v39, v205 offset:16384
.Lsel_grp_17:
	v_xor_b32_e32 v36, v34, v226
	v_xor_b32_e32 v37, v34, v225
	v_xor_b32_e32 v38, v34, v228
	v_xor_b32_e32 v39, v34, v227
	v_min3_u32 v40, v36, v37, v38
	v_min_u32_e32 v40, v40, v39
	v_cmp_gt_u32_e32 vcc, s76, v40
	s_cbranch_vccz .Lsel_grp_18
	v_cmp_gt_u32_e32 vcc, s76, v36
	v_cmp_gt_u32_e64 s[28:29], s76, v37
	v_cmp_gt_u32_e64 s[44:45], s76, v38
	v_cmp_gt_u32_e64 s[74:75], s76, v39
	v_bfe_u32 v36, v226, s16, 8
	v_bfe_u32 v37, v225, s16, 8
	v_bfe_u32 v38, v228, s16, 8
	v_bfe_u32 v39, v227, s16, 8
	v_cndmask_b32_e32 v36, v35, v36, vcc
	v_cndmask_b32_e64 v37, v35, v37, s[28:29]
	v_cndmask_b32_e64 v38, v35, v38, s[44:45]
	v_cndmask_b32_e64 v39, v35, v39, s[74:75]
	v_lshl_add_u32 v36, v36, 6, v0
	v_lshl_add_u32 v37, v37, 6, v0
	v_lshl_add_u32 v38, v38, 6, v0
	v_lshl_add_u32 v39, v39, 6, v0
	ds_add_u32 v36, v205 offset:16384
	ds_add_u32 v37, v205 offset:16384
	ds_add_u32 v38, v205 offset:16384
	ds_add_u32 v39, v205 offset:16384
.Lsel_grp_18:
	v_xor_b32_e32 v36, v34, v11
	v_xor_b32_e32 v37, v34, v10
	v_xor_b32_e32 v38, v34, v13
	v_xor_b32_e32 v39, v34, v12
	v_min3_u32 v40, v36, v37, v38
	v_min_u32_e32 v40, v40, v39
	v_cmp_gt_u32_e32 vcc, s76, v40
	s_cbranch_vccz .Lsel_grp_19
	v_cmp_gt_u32_e32 vcc, s76, v36
	v_cmp_gt_u32_e64 s[28:29], s76, v37
	v_cmp_gt_u32_e64 s[44:45], s76, v38
	v_cmp_gt_u32_e64 s[74:75], s76, v39
	v_bfe_u32 v36, v11, s16, 8
	v_bfe_u32 v37, v10, s16, 8
	v_bfe_u32 v38, v13, s16, 8
	v_bfe_u32 v39, v12, s16, 8
	v_cndmask_b32_e32 v36, v35, v36, vcc
	v_cndmask_b32_e64 v37, v35, v37, s[28:29]
	v_cndmask_b32_e64 v38, v35, v38, s[44:45]
	v_cndmask_b32_e64 v39, v35, v39, s[74:75]
	v_lshl_add_u32 v36, v36, 6, v0
	v_lshl_add_u32 v37, v37, 6, v0
	v_lshl_add_u32 v38, v38, 6, v0
	v_lshl_add_u32 v39, v39, 6, v0
	ds_add_u32 v36, v205 offset:16384
	ds_add_u32 v37, v205 offset:16384
	ds_add_u32 v38, v205 offset:16384
	ds_add_u32 v39, v205 offset:16384
.Lsel_grp_19:
	v_xor_b32_e32 v36, v34, v15
	v_xor_b32_e32 v37, v34, v14
	v_xor_b32_e32 v38, v34, v17
	v_min3_u32 v40, v36, v37, v38
	v_cmp_gt_u32_e32 vcc, s76, v40
	s_cbranch_vccz .Lsel_grp_20
	v_cmp_gt_u32_e32 vcc, s76, v36
	v_cmp_gt_u32_e64 s[28:29], s76, v37
	v_cmp_gt_u32_e64 s[44:45], s76, v38
	v_bfe_u32 v36, v15, s16, 8
	v_bfe_u32 v37, v14, s16, 8
	v_bfe_u32 v38, v17, s16, 8
	v_cndmask_b32_e32 v36, v35, v36, vcc
	v_cndmask_b32_e64 v37, v35, v37, s[28:29]
	v_cndmask_b32_e64 v38, v35, v38, s[44:45]
	v_lshl_add_u32 v36, v36, 6, v0
	v_lshl_add_u32 v37, v37, 6, v0
	v_lshl_add_u32 v38, v38, 6, v0
	ds_add_u32 v36, v205 offset:16384
	ds_add_u32 v37, v205 offset:16384
	ds_add_u32 v38, v205 offset:16384

; #define SEL_HADD(idx_) __hip_atomic_fetch_add(&hist[(idx_)], 1u, __ATOMIC_RELAXED, __HIP_MEMORY_SCOPE_WORKGROUP)
; __device__ __forceinline__ void sel_unit(LAS char* lds, int b, int u, const bf16_t* QI, const bf16_t* KIDX, const float* WIDX, unsigned long long* MASK) {
;     ...
;         for (int j = 0; j < 8; ++j) if (j < nj) {
; #pragma unroll
;             for (int kb = 0; kb < 4; ++kb)
; #pragma unroll
;                 for (int i = 0; i < 4; ++i) { const unsigned k = sc[j][kb][i] | zz; SEL_HADD((((k >> (shift + 8)) == pf) ? ((k >> shift) & 255u) * 16 : 4096u) + q16); __builtin_amdgcn_sched_barrier(0); }
.LBB0_742:
	v_xor_b32_e32 v36, v34, v94
	v_xor_b32_e32 v37, v34, v93
	v_xor_b32_e32 v38, v34, v96
	v_xor_b32_e32 v39, v34, v95
	v_min3_u32 v40, v36, v37, v38
	v_min_u32_e32 v40, v40, v39
	v_cmp_gt_u32_e32 vcc, s76, v40
	s_cbranch_vccz .Lsel_grp_21
	v_cmp_gt_u32_e32 vcc, s76, v36
	v_cmp_gt_u32_e64 s[28:29], s76, v37
	v_cmp_gt_u32_e64 s[44:45], s76, v38
	v_cmp_gt_u32_e64 s[74:75], s76, v39
	v_bfe_u32 v36, v94, s16, 8
	v_bfe_u32 v37, v93, s16, 8
	v_bfe_u32 v38, v96, s16, 8
	v_bfe_u32 v39, v95, s16, 8
	v_cndmask_b32_e32 v36, v35, v36, vcc
	v_cndmask_b32_e64 v37, v35, v37, s[28:29]
	v_cndmask_b32_e64 v38, v35, v38, s[44:45]
	v_cndmask_b32_e64 v39, v35, v39, s[74:75]
	v_lshl_add_u32 v36, v36, 6, v0
	v_lshl_add_u32 v37, v37, 6, v0
	v_lshl_add_u32 v38, v38, 6, v0
	v_lshl_add_u32 v39, v39, 6, v0
	ds_add_u32 v36, v205 offset:16384
	ds_add_u32 v37, v205 offset:16384
	ds_add_u32 v38, v205 offset:16384
	ds_add_u32 v39, v205 offset:16384
.Lsel_grp_21:
	v_xor_b32_e32 v36, v34, v98
	v_xor_b32_e32 v37, v34, v97
	v_xor_b32_e32 v38, v34, v100
	v_xor_b32_e32 v39, v34, v99
	v_min3_u32 v40, v36, v37, v38
	v_min_u32_e32 v40, v40, v39
	v_cmp_gt_u32_e32 vcc, s76, v40
	s_cbranch_vccz .Lsel_grp_22
	v_cmp_gt_u32_e32 vcc, s76, v36
	v_cmp_gt_u32_e64 s[28:29], s76, v37
	v_cmp_gt_u32_e64 s[44:45], s76, v38
	v_cmp_gt_u32_e64 s[74:75], s76, v39
	v_bfe_u32 v36, v98, s16, 8
	v_bfe_u32 v37, v97, s16, 8
	v_bfe_u32 v38, v100, s16, 8
	v_bfe_u32 v39, v99, s16, 8
	v_cndmask_b32_e32 v36, v35, v36, vcc
	v_cndmask_b32_e64 v37, v35, v37, s[28:29]
	v_cndmask_b32_e64 v38, v35, v38, s[44:45]
	v_cndmask_b32_e64 v39, v35, v39, s[74:75]
	v_lshl_add_u32 v36, v36, 6, v0
	v_lshl_add_u32 v37, v37, 6, v0
	v_lshl_add_u32 v38, v38, 6, v0
	v_lshl_add_u32 v39, v39, 6, v0
	ds_add_u32 v36, v205 offset:16384
	ds_add_u32 v37, v205 offset:16384
	ds_add_u32 v38, v205 offset:16384
	ds_add_u32 v39, v205 offset:16384
.Lsel_grp_22:
	v_xor_b32_e32 v36, v34, v102
	v_xor_b32_e32 v37, v34, v101
	v_xor_b32_e32 v38, v34, v104
	v_xor_b32_e32 v39, v34, v103
	v_min3_u32 v40, v36, v37, v38
	v_min_u32_e32 v40, v40, v39
	v_cmp_gt_u32_e32 vcc, s76, v40
	s_cbranch_vccz .Lsel_grp_23
	v_cmp_gt_u32_e32 vcc, s76, v36
	v_cmp_gt_u32_e64 s[28:29], s76, v37
	v_cmp_gt_u32_e64 s[44:45], s76, v38
	v_cmp_gt_u32_e64 s[74:75], s76, v39
	v_bfe_u32 v36, v102, s16, 8
	v_bfe_u32 v37, v101, s16, 8
	v_bfe_u32 v38, v104, s16, 8
	v_bfe_u32 v39, v103, s16, 8
	v_cndmask_b32_e32 v36, v35, v36, vcc
	v_cndmask_b32_e64 v37, v35, v37, s[28:29]
	v_cndmask_b32_e64 v38, v35, v38, s[44:45]
	v_cndmask_b32_e64 v39, v35, v39, s[74:75]
	v_lshl_add_u32 v36, v36, 6, v0
	v_lshl_add_u32 v37, v37, 6, v0
	v_lshl_add_u32 v38, v38, 6, v0
	v_lshl_add_u32 v39, v39, 6, v0
	ds_add_u32 v36, v205 offset:16384
	ds_add_u32 v37, v205 offset:16384
	ds_add_u32 v38, v205 offset:16384
	ds_add_u32 v39, v205 offset:16384
.Lsel_grp_23:
	v_xor_b32_e32 v36, v34, v106
	v_xor_b32_e32 v37, v34, v105
	v_xor_b32_e32 v38, v34, v108
	v_xor_b32_e32 v39, v34, v107
	v_min3_u32 v40, v36, v37, v38
	v_min_u32_e32 v40, v40, v39
	v_cmp_gt_u32_e32 vcc, s76, v40
	s_cbranch_vccz .Lsel_grp_24
	v_cmp_gt_u32_e32 vcc, s76, v36
	v_cmp_gt_u32_e64 s[28:29], s76, v37
	v_cmp_gt_u32_e64 s[44:45], s76, v38
	v_cmp_gt_u32_e64 s[74:75], s76, v39
	v_bfe_u32 v36, v106, s16, 8
	v_bfe_u32 v37, v105, s16, 8
	v_bfe_u32 v38, v108, s16, 8
	v_bfe_u32 v39, v107, s16, 8
	v_cndmask_b32_e32 v36, v35, v36, vcc
	v_cndmask_b32_e64 v37, v35, v37, s[28:29]
	v_cndmask_b32_e64 v38, v35, v38, s[44:45]
	v_cndmask_b32_e64 v39, v35, v39, s[74:75]
	v_lshl_add_u32 v36, v36, 6, v0
	v_lshl_add_u32 v37, v37, 6, v0
	v_lshl_add_u32 v38, v38, 6, v0
	v_lshl_add_u32 v39, v39, 6, v0
	ds_add_u32 v36, v205 offset:16384
	ds_add_u32 v37, v205 offset:16384
	ds_add_u32 v38, v205 offset:16384
	ds_add_u32 v39, v205 offset:16384

; #define SEL_HADD(idx_) __hip_atomic_fetch_add(&hist[(idx_)], 1u, __ATOMIC_RELAXED, __HIP_MEMORY_SCOPE_WORKGROUP)
; __device__ __forceinline__ void sel_unit(LAS char* lds, int b, int u, const bf16_t* QI, const bf16_t* KIDX, const float* WIDX, unsigned long long* MASK) {
;     ...
;         for (int j = 0; j < 8; ++j) if (j < nj) {
; #pragma unroll
;             for (int kb = 0; kb < 4; ++kb)
; #pragma unroll
;                 for (int i = 0; i < 4; ++i) { const unsigned k = sc[j][kb][i] | zz; SEL_HADD((((k >> (shift + 8)) == pf) ? ((k >> shift) & 255u) * 16 : 4096u) + q16); __builtin_amdgcn_sched_barrier(0); }
.LBB0_744:
	v_xor_b32_e32 v36, v34, v126
	v_xor_b32_e32 v37, v34, v125
	v_xor_b32_e32 v38, v34, v128
	v_xor_b32_e32 v39, v34, v127
	v_min3_u32 v40, v36, v37, v38
	v_min_u32_e32 v40, v40, v39
	v_cmp_gt_u32_e32 vcc, s76, v40
	s_cbranch_vccz .Lsel_grp_25
	v_cmp_gt_u32_e32 vcc, s76, v36
	v_cmp_gt_u32_e64 s[28:29], s76, v37
	v_cmp_gt_u32_e64 s[44:45], s76, v38
	v_cmp_gt_u32_e64 s[74:75], s76, v39
	v_bfe_u32 v36, v126, s16, 8
	v_bfe_u32 v37, v125, s16, 8
	v_bfe_u32 v38, v128, s16, 8
	v_bfe_u32 v39, v127, s16, 8
	v_cndmask_b32_e32 v36, v35, v36, vcc
	v_cndmask_b32_e64 v37, v35, v37, s[28:29]
	v_cndmask_b32_e64 v38, v35, v38, s[44:45]
	v_cndmask_b32_e64 v39, v35, v39, s[74:75]
	v_lshl_add_u32 v36, v36, 6, v0
	v_lshl_add_u32 v37, v37, 6, v0
	v_lshl_add_u32 v38, v38, 6, v0
	v_lshl_add_u32 v39, v39, 6, v0
	ds_add_u32 v36, v205 offset:16384
	ds_add_u32 v37, v205 offset:16384
	ds_add_u32 v38, v205 offset:16384
	ds_add_u32 v39, v205 offset:16384
.Lsel_grp_25:
	v_xor_b32_e32 v36, v34, v130
	v_xor_b32_e32 v37, v34, v129
	v_xor_b32_e32 v38, v34, v132
	v_xor_b32_e32 v39, v34, v131
	v_min3_u32 v40, v36, v37, v38
	v_min_u32_e32 v40, v40, v39
	v_cmp_gt_u32_e32 vcc, s76, v40
	s_cbranch_vccz .Lsel_grp_26
	v_cmp_gt_u32_e32 vcc, s76, v36
	v_cmp_gt_u32_e64 s[28:29], s76, v37
	v_cmp_gt_u32_e64 s[44:45], s76, v38
	v_cmp_gt_u32_e64 s[74:75], s76, v39
	v_bfe_u32 v36, v130, s16, 8
	v_bfe_u32 v37, v129, s16, 8
	v_bfe_u32 v38, v132, s16, 8
	v_bfe_u32 v39, v131, s16, 8
	v_cndmask_b32_e32 v36, v35, v36, vcc
	v_cndmask_b32_e64 v37, v35, v37, s[28:29]
	v_cndmask_b32_e64 v38, v35, v38, s[44:45]
	v_cndmask_b32_e64 v39, v35, v39, s[74:75]
	v_lshl_add_u32 v36, v36, 6, v0
	v_lshl_add_u32 v37, v37, 6, v0
	v_lshl_add_u32 v38, v38, 6, v0
	v_lshl_add_u32 v39, v39, 6, v0
	ds_add_u32 v36, v205 offset:16384
	ds_add_u32 v37, v205 offset:16384
	ds_add_u32 v38, v205 offset:16384
	ds_add_u32 v39, v205 offset:16384
.Lsel_grp_26:
	v_xor_b32_e32 v36, v34, v134
	v_xor_b32_e32 v37, v34, v133
	v_xor_b32_e32 v38, v34, v136
	v_xor_b32_e32 v39, v34, v135
	v_min3_u32 v40, v36, v37, v38
	v_min_u32_e32 v40, v40, v39
	v_cmp_gt_u32_e32 vcc, s76, v40
	s_cbranch_vccz .Lsel_grp_27
	v_cmp_gt_u32_e32 vcc, s76, v36
	v_cmp_gt_u32_e64 s[28:29], s76, v37
	v_cmp_gt_u32_e64 s[44:45], s76, v38
	v_cmp_gt_u32_e64 s[74:75], s76, v39
	v_bfe_u32 v36, v134, s16, 8
	v_bfe_u32 v37, v133, s16, 8
	v_bfe_u32 v38, v136, s16, 8
	v_bfe_u32 v39, v135, s16, 8
	v_cndmask_b32_e32 v36, v35, v36, vcc
	v_cndmask_b32_e64 v37, v35, v37, s[28:29]
	v_cndmask_b32_e64 v38, v35, v38, s[44:45]
	v_cndmask_b32_e64 v39, v35, v39, s[74:75]
	v_lshl_add_u32 v36, v36, 6, v0
	v_lshl_add_u32 v37, v37, 6, v0
	v_lshl_add_u32 v38, v38, 6, v0
	v_lshl_add_u32 v39, v39, 6, v0
	ds_add_u32 v36, v205 offset:16384
	ds_add_u32 v37, v205 offset:16384
	ds_add_u32 v38, v205 offset:16384
	ds_add_u32 v39, v205 offset:16384
.Lsel_grp_27:
	v_xor_b32_e32 v36, v34, v139
	v_xor_b32_e32 v37, v34, v138
	v_xor_b32_e32 v38, v34, v141
	v_xor_b32_e32 v39, v34, v140
	v_min3_u32 v40, v36, v37, v38
	v_min_u32_e32 v40, v40, v39
	v_cmp_gt_u32_e32 vcc, s76, v40
	s_cbranch_vccz .Lsel_grp_28
	v_cmp_gt_u32_e32 vcc, s76, v36
	v_cmp_gt_u32_e64 s[28:29], s76, v37
	v_cmp_gt_u32_e64 s[44:45], s76, v38
	v_cmp_gt_u32_e64 s[74:75], s76, v39
	v_bfe_u32 v36, v139, s16, 8
	v_bfe_u32 v37, v138, s16, 8
	v_bfe_u32 v38, v141, s16, 8
	v_bfe_u32 v39, v140, s16, 8
	v_cndmask_b32_e32 v36, v35, v36, vcc
	v_cndmask_b32_e64 v37, v35, v37, s[28:29]
	v_cndmask_b32_e64 v38, v35, v38, s[44:45]
	v_cndmask_b32_e64 v39, v35, v39, s[74:75]
	v_lshl_add_u32 v36, v36, 6, v0
	v_lshl_add_u32 v37, v37, 6, v0
	v_lshl_add_u32 v38, v38, 6, v0
	v_lshl_add_u32 v39, v39, 6, v0
	ds_add_u32 v36, v205 offset:16384
	ds_add_u32 v37, v205 offset:16384
	ds_add_u32 v38, v205 offset:16384
	ds_add_u32 v39, v205 offset:16384

; #define SEL_HADD(idx_) __hip_atomic_fetch_add(&hist[(idx_)], 1u, __ATOMIC_RELAXED, __HIP_MEMORY_SCOPE_WORKGROUP)
; __device__ __forceinline__ void sel_unit(LAS char* lds, int b, int u, const bf16_t* QI, const bf16_t* KIDX, const float* WIDX, unsigned long long* MASK) {
;     ...
;         for (int j = 0; j < 8; ++j) if (j < nj) {
; #pragma unroll
;             for (int kb = 0; kb < 4; ++kb)
; #pragma unroll
;                 for (int i = 0; i < 4; ++i) { const unsigned k = sc[j][kb][i] | zz; SEL_HADD((((k >> (shift + 8)) == pf) ? ((k >> shift) & 255u) * 16 : 4096u) + q16); __builtin_amdgcn_sched_barrier(0); }
.LBB0_746:
	v_xor_b32_e32 v36, v34, v192
	v_xor_b32_e32 v37, v34, v191
	v_xor_b32_e32 v38, v34, v194
	v_xor_b32_e32 v39, v34, v193
	v_min3_u32 v40, v36, v37, v38
	v_min_u32_e32 v40, v40, v39
	v_cmp_gt_u32_e32 vcc, s76, v40
	s_cbranch_vccz .Lsel_grp_29
	v_cmp_gt_u32_e32 vcc, s76, v36
	v_cmp_gt_u32_e64 s[28:29], s76, v37
	v_cmp_gt_u32_e64 s[44:45], s76, v38
	v_cmp_gt_u32_e64 s[74:75], s76, v39
	v_bfe_u32 v36, v192, s16, 8
	v_bfe_u32 v37, v191, s16, 8
	v_bfe_u32 v38, v194, s16, 8
	v_bfe_u32 v39, v193, s16, 8
	v_cndmask_b32_e32 v36, v35, v36, vcc
	v_cndmask_b32_e64 v37, v35, v37, s[28:29]
	v_cndmask_b32_e64 v38, v35, v38, s[44:45]
	v_cndmask_b32_e64 v39, v35, v39, s[74:75]
	v_lshl_add_u32 v36, v36, 6, v0
	v_lshl_add_u32 v37, v37, 6, v0
	v_lshl_add_u32 v38, v38, 6, v0
	v_lshl_add_u32 v39, v39, 6, v0
	ds_add_u32 v36, v205 offset:16384
	ds_add_u32 v37, v205 offset:16384
	ds_add_u32 v38, v205 offset:16384
	ds_add_u32 v39, v205 offset:16384
.Lsel_grp_29:
	v_xor_b32_e32 v36, v34, v196
	v_xor_b32_e32 v37, v34, v195
	v_xor_b32_e32 v38, v34, v198
	v_xor_b32_e32 v39, v34, v197
	v_min3_u32 v40, v36, v37, v38
	v_min_u32_e32 v40, v40, v39
	v_cmp_gt_u32_e32 vcc, s76, v40
	s_cbranch_vccz .Lsel_grp_30
	v_cmp_gt_u32_e32 vcc, s76, v36
	v_cmp_gt_u32_e64 s[28:29], s76, v37
	v_cmp_gt_u32_e64 s[44:45], s76, v38
	v_cmp_gt_u32_e64 s[74:75], s76, v39
	v_bfe_u32 v36, v196, s16, 8
	v_bfe_u32 v37, v195, s16, 8
	v_bfe_u32 v38, v198, s16, 8
	v_bfe_u32 v39, v197, s16, 8
	v_cndmask_b32_e32 v36, v35, v36, vcc
	v_cndmask_b32_e64 v37, v35, v37, s[28:29]
	v_cndmask_b32_e64 v38, v35, v38, s[44:45]
	v_cndmask_b32_e64 v39, v35, v39, s[74:75]
	v_lshl_add_u32 v36, v36, 6, v0
	v_lshl_add_u32 v37, v37, 6, v0
	v_lshl_add_u32 v38, v38, 6, v0
	v_lshl_add_u32 v39, v39, 6, v0
	ds_add_u32 v36, v205 offset:16384
	ds_add_u32 v37, v205 offset:16384
	ds_add_u32 v38, v205 offset:16384
	ds_add_u32 v39, v205 offset:16384
.Lsel_grp_30:
	v_xor_b32_e32 v36, v34, v57
	v_xor_b32_e32 v37, v34, v56
	v_xor_b32_e32 v38, v34, v55
	v_xor_b32_e32 v39, v34, v54
	v_min3_u32 v40, v36, v37, v38
	v_min_u32_e32 v40, v40, v39
	v_cmp_gt_u32_e32 vcc, s76, v40
	s_cbranch_vccz .Lsel_grp_31
	v_cmp_gt_u32_e32 vcc, s76, v36
	v_cmp_gt_u32_e64 s[28:29], s76, v37
	v_cmp_gt_u32_e64 s[44:45], s76, v38
	v_cmp_gt_u32_e64 s[74:75], s76, v39
	v_bfe_u32 v36, v57, s16, 8
	v_bfe_u32 v37, v56, s16, 8
	v_bfe_u32 v38, v55, s16, 8
	v_bfe_u32 v39, v54, s16, 8
	v_cndmask_b32_e32 v36, v35, v36, vcc
	v_cndmask_b32_e64 v37, v35, v37, s[28:29]
	v_cndmask_b32_e64 v38, v35, v38, s[44:45]
	v_cndmask_b32_e64 v39, v35, v39, s[74:75]
	v_lshl_add_u32 v36, v36, 6, v0
	v_lshl_add_u32 v37, v37, 6, v0
	v_lshl_add_u32 v38, v38, 6, v0
	v_lshl_add_u32 v39, v39, 6, v0
	ds_add_u32 v36, v205 offset:16384
	ds_add_u32 v37, v205 offset:16384
	ds_add_u32 v38, v205 offset:16384
	ds_add_u32 v39, v205 offset:16384
.Lsel_grp_31:
	v_xor_b32_e32 v36, v34, v218
	v_xor_b32_e32 v37, v34, v199
	v_xor_b32_e32 v38, v34, v220
	v_xor_b32_e32 v39, v34, v219
	v_min3_u32 v40, v36, v37, v38
	v_min_u32_e32 v40, v40, v39
	v_cmp_gt_u32_e32 vcc, s76, v40
	s_cbranch_vccz .Lsel_grp_32
	v_cmp_gt_u32_e32 vcc, s76, v36
	v_cmp_gt_u32_e64 s[28:29], s76, v37
	v_cmp_gt_u32_e64 s[44:45], s76, v38
	v_cmp_gt_u32_e64 s[74:75], s76, v39
	v_bfe_u32 v36, v218, s16, 8
	v_bfe_u32 v37, v199, s16, 8
	v_bfe_u32 v38, v220, s16, 8
	v_bfe_u32 v39, v219, s16, 8
	v_cndmask_b32_e32 v36, v35, v36, vcc
	v_cndmask_b32_e64 v37, v35, v37, s[28:29]
	v_cndmask_b32_e64 v38, v35, v38, s[44:45]
	v_cndmask_b32_e64 v39, v35, v39, s[74:75]
	v_lshl_add_u32 v36, v36, 6, v0
	v_lshl_add_u32 v37, v37, 6, v0
	v_lshl_add_u32 v38, v38, 6, v0
	v_lshl_add_u32 v39, v39, 6, v0
	ds_add_u32 v36, v205 offset:16384
	ds_add_u32 v37, v205 offset:16384
	ds_add_u32 v38, v205 offset:16384
	ds_add_u32 v39, v205 offset:16384
